# GEMM K-loops: all s_setprio toggles removed (A/B test of whether the per-segment priority flips are load-bearing)
# speedup vs baseline: 1.0042x; 1.0042x over previous
; #define PG8_STAGE(bufoff, gbase, voff) do { _Pragma("unroll") for (int _i = 0; _i < 2; ++_i) \
;         __builtin_amdgcn_global_load_lds((const unsigned*)((const char*)(gbase) + (voff)[_i]), (PG8_LAS unsigned*)(lds + (bufoff) + ldsw + _i * 8192), 16, 0, 0); } while (0)
; #define PG8_LDA(dst, b, h) do { _Pragma("unroll") for (int m = 0; m < 4; ++m) _Pragma("unroll") for (int k = 0; k < 2; ++k) dst[m][k] = *(const PG8_LAS bf16x8*)(lds + PG8_SA(b, h) + aoff + m * 2048 + k * 1024); } while (0)
; #define PG8_LDB(dst, b, h) do { _Pragma("unroll") for (int n = 0; n < 2; ++n) _Pragma("unroll") for (int k = 0; k < 2; ++k) dst[n][k] = *(const PG8_LAS bf16x8*)(lds + PG8_SB(b, h) + boff + n * 2048 + k * 1024); } while (0)
; #define PG8_MMA(ai, bj, At, Bt) do { __builtin_amdgcn_s_setprio(1); _Pragma("unroll") for (int m = 0; m < 4; ++m) _Pragma("unroll") for (int n = 0; n < 2; ++n) _Pragma("unroll") for (int k = 0; k < 2; ++k) \
;         acc[ai][bj][m][n] = __builtin_amdgcn_mfma_f32_16x16x32_bf16(Bt[n][k], At[m][k], acc[ai][bj][m][n], 0, 0, 0); __builtin_amdgcn_s_setprio(0); } while (0)
; #define PG8_WAIT_V(n) asm volatile("s_waitcnt vmcnt(" #n ")" ::: "memory")
; #define PG8_WAIT_L(n) asm volatile("s_waitcnt lgkmcnt(" #n ")" ::: "memory")
; template <class Epi, class Sched, bool ALIGN_EPI = false, bool SP2 = false>
; __device__ __forceinline__ void gemm_phase(PG8_LAS unsigned char* lds, const Gemm g, const Sched& S, const Epi& E) {
;     ...
;             const bool last = (t == nt - 2);
;             const char* a1 = cA + (size_t)(t + 1) * kstep;
;             const char* a2 = last ? nA : cA + (size_t)(t + 2) * kstep; const char* b2 = last ? nB : cB + (size_t)(t + 2) * kstep;
;             const char* a3 = a2 + kstep; const char* b3 = b2 + kstep;
;             if (last && has_next) S.a_ready(nxt);
;             if constexpr (SP2) {
;             PG8_LDB(B0, 0, 0); PG8_LDB(B1, 0, 1); PG8_SCHED; PG8_LDA(At, 0, 0); PG8_STAGE(PG8_SA(1, 1), a1 + hstep, voffA);
;             PG8_WAIT_V(8); PG8_WAIT_L(0); PG8_BAR; PG8_MMA(0, 0, At, B0); PG8_MMA(0, 1, At, B1); PG8_BAR; PG8_SCHED;
;             PG8_LDA(At, 0, 1); PG8_STAGE(PG8_SB(0, 0), b2, voffB); PG8_STAGE(PG8_SB(0, 1), b2 + hstep, voffB); PG8_STAGE(PG8_SA(0, 0), a2, voffA);
;             PG8_WAIT_V(8); PG8_WAIT_L(0); PG8_BAR; PG8_MMA(1, 0, At, B0); PG8_MMA(1, 1, At, B1); PG8_BAR; PG8_SCHED;
.LBB0_417:
	s_add_u32 s0, s40, 0xfff80080
	s_addc_u32 s1, s41, -1
	s_add_i32 s30, 0, 0x10000
	s_cmp_eq_u32 s19, 28
	s_cselect_b32 s5, s7, s1
	s_cselect_b32 s4, s8, s0
	s_cselect_b32 s1, s9, s17
	s_cselect_b32 s0, s14, s15
	s_add_i32 s33, 0, 0x14000
	v_add_u32_e32 v142, s30, v203
	v_add_u32_e32 v158, s33, v203
	ds_read_b128 v[130:133], v142
	ds_read_b128 v[134:137], v142 offset:1024
	ds_read_b128 v[138:141], v142 offset:2048
	ds_read_b128 v[142:145], v142 offset:3072
	ds_read_b128 v[146:149], v158
	ds_read_b128 v[150:153], v158 offset:1024
	ds_read_b128 v[154:157], v158 offset:2048
	ds_read_b128 v[158:161], v158 offset:3072
	v_lshl_add_u64 v[190:191], s[40:41], 0, v[188:189]
	s_add_i32 m0, s67, 0xc000
	ds_read_b128 v[162:165], v209
	ds_read_b128 v[166:169], v209 offset:1024
	ds_read_b128 v[170:173], v209 offset:2048
	ds_read_b128 v[174:177], v209 offset:3072
	ds_read_b128 v[210:213], v209 offset:4096
	ds_read_b128 v[232:235], v209 offset:5120
	ds_read_b128 v[242:245], v209 offset:6144
	ds_read_b128 v[246:249], v209 offset:7168
	global_load_lds_dwordx4 v[190:191], off
	v_lshl_add_u64 v[190:191], s[40:41], 0, v[186:187]
	s_add_i32 m0, s67, 0xe000
	s_nop 0
	global_load_lds_dwordx4 v[190:191], off
	s_waitcnt vmcnt(8)
	s_waitcnt lgkmcnt(0)
	s_barrier
	v_mfma_f32_16x16x32_bf16 v[126:129], v[130:133], v[162:165], v[126:129]
	v_mfma_f32_16x16x32_bf16 v[122:125], v[138:141], v[162:165], v[122:125]
	v_mfma_f32_16x16x32_bf16 v[110:113], v[130:133], v[170:173], v[110:113]
	v_mfma_f32_16x16x32_bf16 v[106:109], v[138:141], v[170:173], v[106:109]
	v_mfma_f32_16x16x32_bf16 v[92:95], v[130:133], v[210:213], v[92:95]
	v_mfma_f32_16x16x32_bf16 v[88:91], v[138:141], v[210:213], v[88:91]
	v_mfma_f32_16x16x32_bf16 v[76:79], v[130:133], v[242:245], v[76:79]
	v_mfma_f32_16x16x32_bf16 v[72:75], v[138:141], v[242:245], v[72:75]
	v_mfma_f32_16x16x32_bf16 v[126:129], v[134:137], v[166:169], v[126:129]
	v_mfma_f32_16x16x32_bf16 v[122:125], v[142:145], v[166:169], v[122:125]
	v_mfma_f32_16x16x32_bf16 v[110:113], v[134:137], v[174:177], v[110:113]
	v_mfma_f32_16x16x32_bf16 v[106:109], v[142:145], v[174:177], v[106:109]
	v_mfma_f32_16x16x32_bf16 v[92:95], v[134:137], v[232:235], v[92:95]
	v_mfma_f32_16x16x32_bf16 v[88:91], v[142:145], v[232:235], v[88:91]
	v_mfma_f32_16x16x32_bf16 v[76:79], v[134:137], v[246:249], v[76:79]
	v_mfma_f32_16x16x32_bf16 v[72:75], v[142:145], v[246:249], v[72:75]
	v_mfma_f32_16x16x32_bf16 v[118:121], v[146:149], v[162:165], v[118:121]
	v_mfma_f32_16x16x32_bf16 v[114:117], v[154:157], v[162:165], v[114:117]
	v_mfma_f32_16x16x32_bf16 v[102:105], v[146:149], v[170:173], v[102:105]
	v_mfma_f32_16x16x32_bf16 v[98:101], v[154:157], v[170:173], v[98:101]
	v_mfma_f32_16x16x32_bf16 v[84:87], v[146:149], v[210:213], v[84:87]
	v_mfma_f32_16x16x32_bf16 v[80:83], v[154:157], v[210:213], v[80:83]
	v_mfma_f32_16x16x32_bf16 v[68:71], v[146:149], v[242:245], v[68:71]
	v_mfma_f32_16x16x32_bf16 v[64:67], v[154:157], v[242:245], v[64:67]
	v_mfma_f32_16x16x32_bf16 v[118:121], v[150:153], v[166:169], v[118:121]
	v_mfma_f32_16x16x32_bf16 v[114:117], v[158:161], v[166:169], v[114:117]
	v_mfma_f32_16x16x32_bf16 v[102:105], v[150:153], v[174:177], v[102:105]
	v_mfma_f32_16x16x32_bf16 v[98:101], v[158:161], v[174:177], v[98:101]
	v_mfma_f32_16x16x32_bf16 v[84:87], v[150:153], v[232:235], v[84:87]
	v_mfma_f32_16x16x32_bf16 v[80:83], v[158:161], v[232:235], v[80:83]
	v_mfma_f32_16x16x32_bf16 v[68:71], v[150:153], v[246:249], v[68:71]
	v_mfma_f32_16x16x32_bf16 v[64:67], v[158:161], v[246:249], v[64:67]
	s_barrier
	s_add_i32 s30, s30, s28
	v_lshl_add_u64 v[190:191], s[0:1], 0, v[96:97]
	s_mov_b32 m0, s30
	ds_read_b128 v[162:165], v209 offset:16384
	ds_read_b128 v[166:169], v209 offset:17408
	ds_read_b128 v[170:173], v209 offset:18432
	ds_read_b128 v[174:177], v209 offset:19456
	ds_read_b128 v[210:213], v209 offset:20480
	ds_read_b128 v[232:235], v209 offset:21504
	ds_read_b128 v[242:245], v209 offset:22528
	ds_read_b128 v[246:249], v209 offset:23552
	global_load_lds_dwordx4 v[190:191], off
	s_add_i32 m0, s30, 0x2000
	s_add_u32 s30, s0, 0x80000
	v_lshl_add_u64 v[204:205], s[0:1], 0, v[178:179]
	s_addc_u32 s31, s1, 0
	s_add_i32 s33, s33, s28
	global_load_lds_dwordx4 v[204:205], off
	v_lshl_add_u64 v[214:215], s[30:31], 0, v[96:97]
	s_mov_b32 m0, s33
	v_lshl_add_u64 v[228:229], s[4:5], 0, v[180:181]
	global_load_lds_dwordx4 v[214:215], off
	v_lshl_add_u64 v[214:215], s[30:31], 0, v[178:179]
	s_add_i32 m0, s33, 0x2000
	s_nop 0
	global_load_lds_dwordx4 v[214:215], off
	v_lshl_add_u64 v[214:215], s[4:5], 0, v[182:183]
	s_mov_b32 m0, s67
	s_nop 0
	global_load_lds_dwordx4 v[214:215], off
	s_mov_b32 m0, s68
	s_nop 0
	global_load_lds_dwordx4 v[228:229], off
	s_waitcnt vmcnt(8)
	s_waitcnt lgkmcnt(0)
	s_barrier
; #define PG8_STAGE(bufoff, gbase, voff) do { _Pragma("unroll") for (int _i = 0; _i < 2; ++_i) \
;         __builtin_amdgcn_global_load_lds((const unsigned*)((const char*)(gbase) + (voff)[_i]), (PG8_LAS unsigned*)(lds + (bufoff) + ldsw + _i * 8192), 16, 0, 0); } while (0)
; #define PG8_LDA(dst, b, h) do { _Pragma("unroll") for (int m = 0; m < 4; ++m) _Pragma("unroll") for (int k = 0; k < 2; ++k) dst[m][k] = *(const PG8_LAS bf16x8*)(lds + PG8_SA(b, h) + aoff + m * 2048 + k * 1024); } while (0)
; #define PG8_LDB(dst, b, h) do { _Pragma("unroll") for (int n = 0; n < 2; ++n) _Pragma("unroll") for (int k = 0; k < 2; ++k) dst[n][k] = *(const PG8_LAS bf16x8*)(lds + PG8_SB(b, h) + boff + n * 2048 + k * 1024); } while (0)
; #define PG8_MMA(ai, bj, At, Bt) do { __builtin_amdgcn_s_setprio(1); _Pragma("unroll") for (int m = 0; m < 4; ++m) _Pragma("unroll") for (int n = 0; n < 2; ++n) _Pragma("unroll") for (int k = 0; k < 2; ++k) \
;         acc[ai][bj][m][n] = __builtin_amdgcn_mfma_f32_16x16x32_bf16(Bt[n][k], At[m][k], acc[ai][bj][m][n], 0, 0, 0); __builtin_amdgcn_s_setprio(0); } while (0)
; #define PG8_WAIT_V(n) asm volatile("s_waitcnt vmcnt(" #n ")" ::: "memory")
; #define PG8_WAIT_L(n) asm volatile("s_waitcnt lgkmcnt(" #n ")" ::: "memory")
; #define PG8_BAR __builtin_amdgcn_s_barrier()
; #define PG8_SCHED __builtin_amdgcn_sched_barrier(0)
; template <class Epi, class Sched, bool ALIGN_EPI = false, bool SP2 = false>
; __device__ __forceinline__ void gemm_phase(PG8_LAS unsigned char* lds, const Gemm g, const Sched& S, const Epi& E) {
;     ...
;             PG8_WAIT_V(8); PG8_WAIT_L(0); PG8_BAR; PG8_MMA(1, 0, At, B0); PG8_MMA(1, 1, At, B1); PG8_BAR; PG8_SCHED;
;             PG8_LDB(B0, 1, 0); PG8_LDB(B1, 1, 1); PG8_SCHED; PG8_LDA(At, 1, 0); PG8_STAGE(PG8_SA(0, 1), a2 + hstep, voffA);
;             PG8_WAIT_V(8); PG8_WAIT_L(0); PG8_BAR; PG8_MMA(0, 0, At, B0); PG8_MMA(0, 1, At, B1); PG8_BAR; PG8_SCHED;
	v_mfma_f32_16x16x32_bf16 v[60:63], v[130:133], v[162:165], v[60:63]
	v_mfma_f32_16x16x32_bf16 v[56:59], v[138:141], v[162:165], v[56:59]
	v_mfma_f32_16x16x32_bf16 v[44:47], v[130:133], v[170:173], v[44:47]
	v_mfma_f32_16x16x32_bf16 v[40:43], v[138:141], v[170:173], v[40:43]
	v_mfma_f32_16x16x32_bf16 v[28:31], v[130:133], v[210:213], v[28:31]
	v_mfma_f32_16x16x32_bf16 v[24:27], v[138:141], v[210:213], v[24:27]
	v_mfma_f32_16x16x32_bf16 v[12:15], v[130:133], v[242:245], v[12:15]
	v_mfma_f32_16x16x32_bf16 v[8:11], v[138:141], v[242:245], v[8:11]
	v_mfma_f32_16x16x32_bf16 v[60:63], v[134:137], v[166:169], v[60:63]
	v_mfma_f32_16x16x32_bf16 v[56:59], v[142:145], v[166:169], v[56:59]
	v_mfma_f32_16x16x32_bf16 v[44:47], v[134:137], v[174:177], v[44:47]
	v_mfma_f32_16x16x32_bf16 v[40:43], v[142:145], v[174:177], v[40:43]
	v_mfma_f32_16x16x32_bf16 v[28:31], v[134:137], v[232:235], v[28:31]
	v_mfma_f32_16x16x32_bf16 v[24:27], v[142:145], v[232:235], v[24:27]
	v_mfma_f32_16x16x32_bf16 v[12:15], v[134:137], v[246:249], v[12:15]
	v_mfma_f32_16x16x32_bf16 v[8:11], v[142:145], v[246:249], v[8:11]
	v_mfma_f32_16x16x32_bf16 v[52:55], v[146:149], v[162:165], v[52:55]
	v_mfma_f32_16x16x32_bf16 v[48:51], v[154:157], v[162:165], v[48:51]
	v_mfma_f32_16x16x32_bf16 v[36:39], v[146:149], v[170:173], v[36:39]
	v_mfma_f32_16x16x32_bf16 v[32:35], v[154:157], v[170:173], v[32:35]
	v_mfma_f32_16x16x32_bf16 v[20:23], v[146:149], v[210:213], v[20:23]
	v_mfma_f32_16x16x32_bf16 v[16:19], v[154:157], v[210:213], v[16:19]
	v_mfma_f32_16x16x32_bf16 v[4:7], v[146:149], v[242:245], v[4:7]
	v_mfma_f32_16x16x32_bf16 v[0:3], v[154:157], v[242:245], v[0:3]
	v_mfma_f32_16x16x32_bf16 v[52:55], v[150:153], v[166:169], v[52:55]
	v_mfma_f32_16x16x32_bf16 v[48:51], v[158:161], v[166:169], v[48:51]
	v_mfma_f32_16x16x32_bf16 v[36:39], v[150:153], v[174:177], v[36:39]
	v_mfma_f32_16x16x32_bf16 v[32:35], v[158:161], v[174:177], v[32:35]
	v_mfma_f32_16x16x32_bf16 v[20:23], v[150:153], v[232:235], v[20:23]
	v_mfma_f32_16x16x32_bf16 v[16:19], v[158:161], v[232:235], v[16:19]
	v_mfma_f32_16x16x32_bf16 v[4:7], v[150:153], v[246:249], v[4:7]
	v_mfma_f32_16x16x32_bf16 v[0:3], v[158:161], v[246:249], v[0:3]
	s_barrier
	s_add_i32 s30, 0, 0x18000
	s_add_i32 s31, 0, 0x1c000
	v_add_u32_e32 v142, s30, v203
	v_add_u32_e32 v158, s31, v203
	ds_read_b128 v[130:133], v142
	ds_read_b128 v[134:137], v142 offset:1024
	ds_read_b128 v[138:141], v142 offset:2048
	ds_read_b128 v[142:145], v142 offset:3072
	ds_read_b128 v[146:149], v158
	ds_read_b128 v[150:153], v158 offset:1024
	ds_read_b128 v[154:157], v158 offset:2048
	ds_read_b128 v[158:161], v158 offset:3072
	s_add_u32 s4, s4, 0x80000
	s_addc_u32 s5, s5, 0
	s_mov_b32 m0, s69
	v_lshl_add_u64 v[230:231], s[4:5], 0, v[182:183]
	ds_read_b128 v[162:165], v209 offset:32768
	ds_read_b128 v[166:169], v209 offset:33792
	ds_read_b128 v[170:173], v209 offset:34816
	ds_read_b128 v[174:177], v209 offset:35840
	ds_read_b128 v[210:213], v209 offset:36864
	ds_read_b128 v[232:235], v209 offset:37888
	ds_read_b128 v[242:245], v209 offset:38912
	ds_read_b128 v[246:249], v209 offset:39936
	global_load_lds_dwordx4 v[230:231], off
	v_lshl_add_u64 v[230:231], s[4:5], 0, v[180:181]
	s_mov_b32 m0, s72
	s_nop 0
	global_load_lds_dwordx4 v[230:231], off
	s_waitcnt vmcnt(8)
	s_waitcnt lgkmcnt(0)
	s_barrier
	v_mfma_f32_16x16x32_bf16 v[126:129], v[130:133], v[162:165], v[126:129]
	v_mfma_f32_16x16x32_bf16 v[122:125], v[138:141], v[162:165], v[122:125]
	v_mfma_f32_16x16x32_bf16 v[110:113], v[130:133], v[170:173], v[110:113]
	v_mfma_f32_16x16x32_bf16 v[106:109], v[138:141], v[170:173], v[106:109]
	v_mfma_f32_16x16x32_bf16 v[92:95], v[130:133], v[210:213], v[92:95]
	v_mfma_f32_16x16x32_bf16 v[88:91], v[138:141], v[210:213], v[88:91]
	v_mfma_f32_16x16x32_bf16 v[76:79], v[130:133], v[242:245], v[76:79]
	v_mfma_f32_16x16x32_bf16 v[72:75], v[138:141], v[242:245], v[72:75]
	v_mfma_f32_16x16x32_bf16 v[126:129], v[134:137], v[166:169], v[126:129]
	v_mfma_f32_16x16x32_bf16 v[122:125], v[142:145], v[166:169], v[122:125]
	v_mfma_f32_16x16x32_bf16 v[110:113], v[134:137], v[174:177], v[110:113]
	v_mfma_f32_16x16x32_bf16 v[106:109], v[142:145], v[174:177], v[106:109]
	v_mfma_f32_16x16x32_bf16 v[92:95], v[134:137], v[232:235], v[92:95]
	v_mfma_f32_16x16x32_bf16 v[88:91], v[142:145], v[232:235], v[88:91]
	v_mfma_f32_16x16x32_bf16 v[76:79], v[134:137], v[246:249], v[76:79]
	v_mfma_f32_16x16x32_bf16 v[72:75], v[142:145], v[246:249], v[72:75]
	v_mfma_f32_16x16x32_bf16 v[118:121], v[146:149], v[162:165], v[118:121]
	v_mfma_f32_16x16x32_bf16 v[114:117], v[154:157], v[162:165], v[114:117]
	v_mfma_f32_16x16x32_bf16 v[102:105], v[146:149], v[170:173], v[102:105]
	v_mfma_f32_16x16x32_bf16 v[98:101], v[154:157], v[170:173], v[98:101]
	v_mfma_f32_16x16x32_bf16 v[84:87], v[146:149], v[210:213], v[84:87]
	v_mfma_f32_16x16x32_bf16 v[80:83], v[154:157], v[210:213], v[80:83]
	v_mfma_f32_16x16x32_bf16 v[68:71], v[146:149], v[242:245], v[68:71]
	v_mfma_f32_16x16x32_bf16 v[64:67], v[154:157], v[242:245], v[64:67]
	v_mfma_f32_16x16x32_bf16 v[118:121], v[150:153], v[166:169], v[118:121]
	v_mfma_f32_16x16x32_bf16 v[114:117], v[158:161], v[166:169], v[114:117]
	v_mfma_f32_16x16x32_bf16 v[102:105], v[150:153], v[174:177], v[102:105]
	v_mfma_f32_16x16x32_bf16 v[98:101], v[158:161], v[174:177], v[98:101]
	v_mfma_f32_16x16x32_bf16 v[84:87], v[150:153], v[232:235], v[84:87]
	v_mfma_f32_16x16x32_bf16 v[80:83], v[158:161], v[232:235], v[80:83]
	v_mfma_f32_16x16x32_bf16 v[68:71], v[150:153], v[246:249], v[68:71]
	v_mfma_f32_16x16x32_bf16 v[64:67], v[158:161], v[246:249], v[64:67]
	s_barrier
; #define PG8_STAGE(bufoff, gbase, voff) do { _Pragma("unroll") for (int _i = 0; _i < 2; ++_i) \
;         __builtin_amdgcn_global_load_lds((const unsigned*)((const char*)(gbase) + (voff)[_i]), (PG8_LAS unsigned*)(lds + (bufoff) + ldsw + _i * 8192), 16, 0, 0); } while (0)
; #define PG8_LDA(dst, b, h) do { _Pragma("unroll") for (int m = 0; m < 4; ++m) _Pragma("unroll") for (int k = 0; k < 2; ++k) dst[m][k] = *(const PG8_LAS bf16x8*)(lds + PG8_SA(b, h) + aoff + m * 2048 + k * 1024); } while (0)
; #define PG8_MMA(ai, bj, At, Bt) do { __builtin_amdgcn_s_setprio(1); _Pragma("unroll") for (int m = 0; m < 4; ++m) _Pragma("unroll") for (int n = 0; n < 2; ++n) _Pragma("unroll") for (int k = 0; k < 2; ++k) \
;         acc[ai][bj][m][n] = __builtin_amdgcn_mfma_f32_16x16x32_bf16(Bt[n][k], At[m][k], acc[ai][bj][m][n], 0, 0, 0); __builtin_amdgcn_s_setprio(0); } while (0)
; #define PG8_WAIT_V(n) asm volatile("s_waitcnt vmcnt(" #n ")" ::: "memory")
; #define PG8_WAIT_L(n) asm volatile("s_waitcnt lgkmcnt(" #n ")" ::: "memory")
; #define PG8_BAR __builtin_amdgcn_s_barrier()
; #define PG8_SCHED __builtin_amdgcn_sched_barrier(0)
; template <class Epi, class Sched, bool ALIGN_EPI = false, bool SP2 = false>
; __device__ __forceinline__ void gemm_phase(PG8_LAS unsigned char* lds, const Gemm g, const Sched& S, const Epi& E) {
;     ...
;             PG8_LDA(At, 1, 1); PG8_STAGE(PG8_SB(1, 0), b3, voffB); PG8_STAGE(PG8_SB(1, 1), b3 + hstep, voffB); PG8_STAGE(PG8_SA(1, 0), a3, voffA);
;             PG8_WAIT_V(8); PG8_WAIT_L(0); PG8_BAR; PG8_MMA(1, 0, At, B0); PG8_MMA(1, 1, At, B1); PG8_BAR; PG8_SCHED;
	s_add_i32 s4, s30, s28
	v_lshl_add_u64 v[190:191], v[190:191], 0, s[20:21]
	s_mov_b32 m0, s4
	ds_read_b128 v[162:165], v209 offset:49152
	ds_read_b128 v[166:169], v209 offset:50176
	ds_read_b128 v[170:173], v209 offset:51200
	ds_read_b128 v[174:177], v209 offset:52224
	ds_read_b128 v[210:213], v209 offset:53248
	ds_read_b128 v[232:235], v209 offset:54272
	ds_read_b128 v[242:245], v209 offset:55296
	ds_read_b128 v[246:249], v209 offset:56320
	global_load_lds_dwordx4 v[190:191], off
	s_add_i32 m0, s4, 0x2000
	s_add_u32 s0, s0, 0x80080
	v_lshl_add_u64 v[190:191], v[204:205], 0, s[20:21]
	s_addc_u32 s1, s1, 0
	s_add_i32 s4, s31, s28
	global_load_lds_dwordx4 v[190:191], off
	v_lshl_add_u64 v[190:191], s[0:1], 0, v[96:97]
	s_mov_b32 m0, s4
	s_nop 0
	global_load_lds_dwordx4 v[190:191], off
	v_lshl_add_u64 v[190:191], s[0:1], 0, v[178:179]
	s_add_i32 m0, s4, 0x2000
	s_nop 0
	global_load_lds_dwordx4 v[190:191], off
	v_lshl_add_u64 v[190:191], v[214:215], 0, s[20:21]
	s_mov_b32 m0, s74
	s_nop 0
	global_load_lds_dwordx4 v[190:191], off
	v_lshl_add_u64 v[190:191], v[228:229], 0, s[20:21]
	s_mov_b32 m0, s75
	s_nop 0
	global_load_lds_dwordx4 v[190:191], off
	s_waitcnt vmcnt(8)
	s_waitcnt lgkmcnt(0)
	s_barrier
	v_mfma_f32_16x16x32_bf16 v[60:63], v[130:133], v[162:165], v[60:63]
	v_mfma_f32_16x16x32_bf16 v[56:59], v[138:141], v[162:165], v[56:59]
	v_mfma_f32_16x16x32_bf16 v[44:47], v[130:133], v[170:173], v[44:47]
	v_mfma_f32_16x16x32_bf16 v[40:43], v[138:141], v[170:173], v[40:43]
	v_mfma_f32_16x16x32_bf16 v[28:31], v[130:133], v[210:213], v[28:31]
	v_mfma_f32_16x16x32_bf16 v[24:27], v[138:141], v[210:213], v[24:27]
	v_mfma_f32_16x16x32_bf16 v[12:15], v[130:133], v[242:245], v[12:15]
	v_mfma_f32_16x16x32_bf16 v[8:11], v[138:141], v[242:245], v[8:11]
	v_mfma_f32_16x16x32_bf16 v[60:63], v[134:137], v[166:169], v[60:63]
	v_mfma_f32_16x16x32_bf16 v[56:59], v[142:145], v[166:169], v[56:59]
	v_mfma_f32_16x16x32_bf16 v[44:47], v[134:137], v[174:177], v[44:47]
	v_mfma_f32_16x16x32_bf16 v[40:43], v[142:145], v[174:177], v[40:43]
	v_mfma_f32_16x16x32_bf16 v[28:31], v[134:137], v[232:235], v[28:31]
	v_mfma_f32_16x16x32_bf16 v[24:27], v[142:145], v[232:235], v[24:27]
	v_mfma_f32_16x16x32_bf16 v[12:15], v[134:137], v[246:249], v[12:15]
	v_mfma_f32_16x16x32_bf16 v[8:11], v[142:145], v[246:249], v[8:11]
	v_mfma_f32_16x16x32_bf16 v[52:55], v[146:149], v[162:165], v[52:55]
	v_mfma_f32_16x16x32_bf16 v[48:51], v[154:157], v[162:165], v[48:51]
	v_mfma_f32_16x16x32_bf16 v[36:39], v[146:149], v[170:173], v[36:39]
	v_mfma_f32_16x16x32_bf16 v[32:35], v[154:157], v[170:173], v[32:35]
	v_mfma_f32_16x16x32_bf16 v[20:23], v[146:149], v[210:213], v[20:23]
	v_mfma_f32_16x16x32_bf16 v[16:19], v[154:157], v[210:213], v[16:19]
	v_mfma_f32_16x16x32_bf16 v[4:7], v[146:149], v[242:245], v[4:7]
	v_mfma_f32_16x16x32_bf16 v[0:3], v[154:157], v[242:245], v[0:3]
	v_mfma_f32_16x16x32_bf16 v[52:55], v[150:153], v[166:169], v[52:55]
	v_mfma_f32_16x16x32_bf16 v[48:51], v[158:161], v[166:169], v[48:51]
	v_mfma_f32_16x16x32_bf16 v[36:39], v[150:153], v[174:177], v[36:39]
	v_mfma_f32_16x16x32_bf16 v[32:35], v[158:161], v[174:177], v[32:35]
	v_mfma_f32_16x16x32_bf16 v[20:23], v[150:153], v[232:235], v[20:23]
	v_mfma_f32_16x16x32_bf16 v[16:19], v[158:161], v[232:235], v[16:19]
	v_mfma_f32_16x16x32_bf16 v[4:7], v[150:153], v[246:249], v[4:7]
	v_mfma_f32_16x16x32_bf16 v[0:3], v[158:161], v[246:249], v[0:3]
	s_barrier
	s_add_i32 s19, s19, 2
	s_add_u32 s15, s15, 0x100
	s_addc_u32 s17, s17, 0
	s_add_u32 s40, s40, 0x100
	s_addc_u32 s41, s41, 0
	s_cmp_gt_u32 s19, 29
	s_cbranch_scc0 .LBB0_417
	s_and_b64 vcc, exec, s[34:35]
	s_cbranch_vccz .LBB0_420
	s_barrier

; #define PG8_STAGE(bufoff, gbase, voff) do { _Pragma("unroll") for (int _i = 0; _i < 2; ++_i) \
;         __builtin_amdgcn_global_load_lds((const unsigned*)((const char*)(gbase) + (voff)[_i]), (PG8_LAS unsigned*)(lds + (bufoff) + ldsw + _i * 8192), 16, 0, 0); } while (0)
; #define PG8_LDA(dst, b, h) do { _Pragma("unroll") for (int m = 0; m < 4; ++m) _Pragma("unroll") for (int k = 0; k < 2; ++k) dst[m][k] = *(const PG8_LAS bf16x8*)(lds + PG8_SA(b, h) + aoff + m * 2048 + k * 1024); } while (0)
; #define PG8_LDB(dst, b, h) do { _Pragma("unroll") for (int n = 0; n < 2; ++n) _Pragma("unroll") for (int k = 0; k < 2; ++k) dst[n][k] = *(const PG8_LAS bf16x8*)(lds + PG8_SB(b, h) + boff + n * 2048 + k * 1024); } while (0)
; #define PG8_MMA(ai, bj, At, Bt) do { __builtin_amdgcn_s_setprio(1); _Pragma("unroll") for (int m = 0; m < 4; ++m) _Pragma("unroll") for (int n = 0; n < 2; ++n) _Pragma("unroll") for (int k = 0; k < 2; ++k) \
;         acc[ai][bj][m][n] = __builtin_amdgcn_mfma_f32_16x16x32_bf16(Bt[n][k], At[m][k], acc[ai][bj][m][n], 0, 0, 0); __builtin_amdgcn_s_setprio(0); } while (0)
; #define PG8_WAIT_V(n) asm volatile("s_waitcnt vmcnt(" #n ")" ::: "memory")
; #define PG8_WAIT_L(n) asm volatile("s_waitcnt lgkmcnt(" #n ")" ::: "memory")
; template <class Epi, class Sched, bool ALIGN_EPI = false, bool SP2 = false>
; __device__ __forceinline__ void gemm_phase(PG8_LAS unsigned char* lds, const Gemm g, const Sched& S, const Epi& E) {
;     ...
;             const bool last = (t == nt - 2);
;             const char* a1 = cA + (size_t)(t + 1) * kstep;
;             const char* a2 = last ? nA : cA + (size_t)(t + 2) * kstep; const char* b2 = last ? nB : cB + (size_t)(t + 2) * kstep;
;             const char* a3 = a2 + kstep; const char* b3 = b2 + kstep;
;             if (last && has_next) S.a_ready(nxt);
;             if constexpr (SP2) {
;             PG8_LDB(B0, 0, 0); PG8_LDB(B1, 0, 1); PG8_SCHED; PG8_LDA(At, 0, 0); PG8_STAGE(PG8_SA(1, 1), a1 + hstep, voffA);
;             PG8_WAIT_V(8); PG8_WAIT_L(0); PG8_BAR; PG8_MMA(0, 0, At, B0); PG8_MMA(0, 1, At, B1); PG8_BAR; PG8_SCHED;
;             PG8_LDA(At, 0, 1); PG8_STAGE(PG8_SB(0, 0), b2, voffB); PG8_STAGE(PG8_SB(0, 1), b2 + hstep, voffB); PG8_STAGE(PG8_SA(0, 0), a2, voffA);
;             PG8_WAIT_V(8); PG8_WAIT_L(0); PG8_BAR; PG8_MMA(1, 0, At, B0); PG8_MMA(1, 1, At, B1); PG8_BAR; PG8_SCHED;
.LBB0_447:
	s_add_i32 s28, s0, 2
	s_add_u32 s30, s66, 0x80
	s_addc_u32 s1, s67, 0
	s_add_i32 s33, 0, 0x10000
	s_cmp_eq_u32 s59, s0
	s_cselect_b32 s1, s43, s1
	s_cselect_b32 s0, s42, s30
	s_cselect_b32 s31, s65, s23
	s_cselect_b32 s30, s64, s17
	s_add_i32 s52, 0, 0x14000
	v_add_u32_e32 v126, s33, v232
	v_add_u32_e32 v158, s52, v232
	ds_read_b128 v[98:101], v126
	ds_read_b128 v[106:109], v126 offset:1024
	ds_read_b128 v[118:121], v126 offset:2048
	ds_read_b128 v[126:129], v126 offset:3072
	ds_read_b128 v[138:141], v158
	ds_read_b128 v[142:145], v158 offset:1024
	ds_read_b128 v[150:153], v158 offset:2048
	ds_read_b128 v[158:161], v158 offset:3072
	v_lshl_add_u64 v[212:213], s[66:67], 0, v[210:211]
	s_add_i32 m0, s4, 0xc000
	ds_read_b128 v[162:165], v234
	ds_read_b128 v[166:169], v234 offset:1024
	ds_read_b128 v[170:173], v234 offset:2048
	ds_read_b128 v[174:177], v234 offset:3072
	ds_read_b128 v[178:181], v234 offset:4096
	ds_read_b128 v[182:185], v234 offset:5120
	ds_read_b128 v[186:189], v234 offset:6144
	ds_read_b128 v[190:193], v234 offset:7168
	global_load_lds_dwordx4 v[212:213], off
	v_lshl_add_u64 v[212:213], s[66:67], 0, v[208:209]
	s_add_i32 m0, s4, 0xe000
	s_nop 0
	global_load_lds_dwordx4 v[212:213], off
	s_waitcnt vmcnt(8)
	s_waitcnt lgkmcnt(0)
	s_barrier
	v_mfma_f32_16x16x32_bf16 v[154:157], v[98:101], v[162:165], v[154:157]
	v_mfma_f32_16x16x32_bf16 v[146:149], v[118:121], v[162:165], v[146:149]
	v_mfma_f32_16x16x32_bf16 v[122:125], v[98:101], v[170:173], v[122:125]
	v_mfma_f32_16x16x32_bf16 v[114:117], v[118:121], v[170:173], v[114:117]
	v_mfma_f32_16x16x32_bf16 v[92:95], v[98:101], v[178:181], v[92:95]
	v_mfma_f32_16x16x32_bf16 v[88:91], v[118:121], v[178:181], v[88:91]
	v_mfma_f32_16x16x32_bf16 v[76:79], v[98:101], v[186:189], v[76:79]
	v_mfma_f32_16x16x32_bf16 v[72:75], v[118:121], v[186:189], v[72:75]
	v_mfma_f32_16x16x32_bf16 v[154:157], v[106:109], v[166:169], v[154:157]
	v_mfma_f32_16x16x32_bf16 v[146:149], v[126:129], v[166:169], v[146:149]
	v_mfma_f32_16x16x32_bf16 v[122:125], v[106:109], v[174:177], v[122:125]
	v_mfma_f32_16x16x32_bf16 v[114:117], v[126:129], v[174:177], v[114:117]
	v_mfma_f32_16x16x32_bf16 v[92:95], v[106:109], v[182:185], v[92:95]
	v_mfma_f32_16x16x32_bf16 v[88:91], v[126:129], v[182:185], v[88:91]
	v_mfma_f32_16x16x32_bf16 v[76:79], v[106:109], v[190:193], v[76:79]
	v_mfma_f32_16x16x32_bf16 v[72:75], v[126:129], v[190:193], v[72:75]
	v_mfma_f32_16x16x32_bf16 v[134:137], v[138:141], v[162:165], v[134:137]
	v_mfma_f32_16x16x32_bf16 v[130:133], v[150:153], v[162:165], v[130:133]
	v_mfma_f32_16x16x32_bf16 v[110:113], v[138:141], v[170:173], v[110:113]
	v_mfma_f32_16x16x32_bf16 v[102:105], v[150:153], v[170:173], v[102:105]
	v_mfma_f32_16x16x32_bf16 v[84:87], v[138:141], v[178:181], v[84:87]
	v_mfma_f32_16x16x32_bf16 v[80:83], v[150:153], v[178:181], v[80:83]
	v_mfma_f32_16x16x32_bf16 v[68:71], v[138:141], v[186:189], v[68:71]
	v_mfma_f32_16x16x32_bf16 v[64:67], v[150:153], v[186:189], v[64:67]
	v_mfma_f32_16x16x32_bf16 v[134:137], v[142:145], v[166:169], v[134:137]
	v_mfma_f32_16x16x32_bf16 v[130:133], v[158:161], v[166:169], v[130:133]
	v_mfma_f32_16x16x32_bf16 v[110:113], v[142:145], v[174:177], v[110:113]
	v_mfma_f32_16x16x32_bf16 v[102:105], v[158:161], v[174:177], v[102:105]
	v_mfma_f32_16x16x32_bf16 v[84:87], v[142:145], v[182:185], v[84:87]
	v_mfma_f32_16x16x32_bf16 v[80:83], v[158:161], v[182:185], v[80:83]
	v_mfma_f32_16x16x32_bf16 v[68:71], v[142:145], v[190:193], v[68:71]
	v_mfma_f32_16x16x32_bf16 v[64:67], v[158:161], v[190:193], v[64:67]
	s_barrier
	s_add_i32 s33, s33, s2
	v_lshl_add_u64 v[212:213], s[30:31], 0, v[96:97]
	s_mov_b32 m0, s33
	ds_read_b128 v[162:165], v234 offset:16384
	ds_read_b128 v[166:169], v234 offset:17408
	ds_read_b128 v[170:173], v234 offset:18432
	ds_read_b128 v[174:177], v234 offset:19456
	ds_read_b128 v[178:181], v234 offset:20480
	ds_read_b128 v[182:185], v234 offset:21504
	ds_read_b128 v[186:189], v234 offset:22528
	ds_read_b128 v[190:193], v234 offset:23552
	global_load_lds_dwordx4 v[212:213], off
	s_add_i32 m0, s33, 0x2000
	v_lshl_add_u64 v[214:215], s[30:31], 0, v[202:203]
	s_add_u32 s30, s30, s22
	s_addc_u32 s31, s31, 0
	s_add_i32 s33, s52, s2
	global_load_lds_dwordx4 v[214:215], off
	v_lshl_add_u64 v[228:229], s[30:31], 0, v[96:97]
	s_mov_b32 m0, s33
	v_lshl_add_u64 v[236:237], s[30:31], 0, v[202:203]
	global_load_lds_dwordx4 v[228:229], off
	s_add_i32 m0, s33, 0x2000
	v_lshl_add_u64 v[242:243], s[0:1], 0, v[206:207]
	global_load_lds_dwordx4 v[236:237], off
	s_mov_b32 m0, s4
	v_lshl_add_u64 v[244:245], s[0:1], 0, v[204:205]
	global_load_lds_dwordx4 v[242:243], off
	s_mov_b32 m0, s5
	s_nop 0
	global_load_lds_dwordx4 v[244:245], off
	s_waitcnt vmcnt(8)
	s_waitcnt lgkmcnt(0)
	s_barrier
; #define PG8_STAGE(bufoff, gbase, voff) do { _Pragma("unroll") for (int _i = 0; _i < 2; ++_i) \
;         __builtin_amdgcn_global_load_lds((const unsigned*)((const char*)(gbase) + (voff)[_i]), (PG8_LAS unsigned*)(lds + (bufoff) + ldsw + _i * 8192), 16, 0, 0); } while (0)
; #define PG8_LDA(dst, b, h) do { _Pragma("unroll") for (int m = 0; m < 4; ++m) _Pragma("unroll") for (int k = 0; k < 2; ++k) dst[m][k] = *(const PG8_LAS bf16x8*)(lds + PG8_SA(b, h) + aoff + m * 2048 + k * 1024); } while (0)
; #define PG8_LDB(dst, b, h) do { _Pragma("unroll") for (int n = 0; n < 2; ++n) _Pragma("unroll") for (int k = 0; k < 2; ++k) dst[n][k] = *(const PG8_LAS bf16x8*)(lds + PG8_SB(b, h) + boff + n * 2048 + k * 1024); } while (0)
; #define PG8_MMA(ai, bj, At, Bt) do { __builtin_amdgcn_s_setprio(1); _Pragma("unroll") for (int m = 0; m < 4; ++m) _Pragma("unroll") for (int n = 0; n < 2; ++n) _Pragma("unroll") for (int k = 0; k < 2; ++k) \
;         acc[ai][bj][m][n] = __builtin_amdgcn_mfma_f32_16x16x32_bf16(Bt[n][k], At[m][k], acc[ai][bj][m][n], 0, 0, 0); __builtin_amdgcn_s_setprio(0); } while (0)
; #define PG8_WAIT_V(n) asm volatile("s_waitcnt vmcnt(" #n ")" ::: "memory")
; #define PG8_WAIT_L(n) asm volatile("s_waitcnt lgkmcnt(" #n ")" ::: "memory")
; #define PG8_BAR __builtin_amdgcn_s_barrier()
; #define PG8_SCHED __builtin_amdgcn_sched_barrier(0)
; template <class Epi, class Sched, bool ALIGN_EPI = false, bool SP2 = false>
; __device__ __forceinline__ void gemm_phase(PG8_LAS unsigned char* lds, const Gemm g, const Sched& S, const Epi& E) {
;     ...
;             PG8_WAIT_V(8); PG8_WAIT_L(0); PG8_BAR; PG8_MMA(1, 0, At, B0); PG8_MMA(1, 1, At, B1); PG8_BAR; PG8_SCHED;
;             PG8_LDB(B0, 1, 0); PG8_LDB(B1, 1, 1); PG8_SCHED; PG8_LDA(At, 1, 0); PG8_STAGE(PG8_SA(0, 1), a2 + hstep, voffA);
;             PG8_WAIT_V(8); PG8_WAIT_L(0); PG8_BAR; PG8_MMA(0, 0, At, B0); PG8_MMA(0, 1, At, B1); PG8_BAR; PG8_SCHED;
	v_mfma_f32_16x16x32_bf16 v[60:63], v[98:101], v[162:165], v[60:63]
	v_mfma_f32_16x16x32_bf16 v[56:59], v[118:121], v[162:165], v[56:59]
	v_mfma_f32_16x16x32_bf16 v[44:47], v[98:101], v[170:173], v[44:47]
	v_mfma_f32_16x16x32_bf16 v[40:43], v[118:121], v[170:173], v[40:43]
	v_mfma_f32_16x16x32_bf16 v[28:31], v[98:101], v[178:181], v[28:31]
	v_mfma_f32_16x16x32_bf16 v[24:27], v[118:121], v[178:181], v[24:27]
	v_mfma_f32_16x16x32_bf16 v[12:15], v[98:101], v[186:189], v[12:15]
	v_mfma_f32_16x16x32_bf16 v[8:11], v[118:121], v[186:189], v[8:11]
	v_mfma_f32_16x16x32_bf16 v[60:63], v[106:109], v[166:169], v[60:63]
	v_mfma_f32_16x16x32_bf16 v[56:59], v[126:129], v[166:169], v[56:59]
	v_mfma_f32_16x16x32_bf16 v[44:47], v[106:109], v[174:177], v[44:47]
	v_mfma_f32_16x16x32_bf16 v[40:43], v[126:129], v[174:177], v[40:43]
	v_mfma_f32_16x16x32_bf16 v[28:31], v[106:109], v[182:185], v[28:31]
	v_mfma_f32_16x16x32_bf16 v[24:27], v[126:129], v[182:185], v[24:27]
	v_mfma_f32_16x16x32_bf16 v[12:15], v[106:109], v[190:193], v[12:15]
	v_mfma_f32_16x16x32_bf16 v[8:11], v[126:129], v[190:193], v[8:11]
	v_mfma_f32_16x16x32_bf16 v[52:55], v[138:141], v[162:165], v[52:55]
	v_mfma_f32_16x16x32_bf16 v[48:51], v[150:153], v[162:165], v[48:51]
	v_mfma_f32_16x16x32_bf16 v[36:39], v[138:141], v[170:173], v[36:39]
	v_mfma_f32_16x16x32_bf16 v[32:35], v[150:153], v[170:173], v[32:35]
	v_mfma_f32_16x16x32_bf16 v[20:23], v[138:141], v[178:181], v[20:23]
	v_mfma_f32_16x16x32_bf16 v[16:19], v[150:153], v[178:181], v[16:19]
	v_mfma_f32_16x16x32_bf16 v[4:7], v[138:141], v[186:189], v[4:7]
	v_mfma_f32_16x16x32_bf16 v[0:3], v[150:153], v[186:189], v[0:3]
	v_mfma_f32_16x16x32_bf16 v[52:55], v[142:145], v[166:169], v[52:55]
	v_mfma_f32_16x16x32_bf16 v[48:51], v[158:161], v[166:169], v[48:51]
	v_mfma_f32_16x16x32_bf16 v[36:39], v[142:145], v[174:177], v[36:39]
	v_mfma_f32_16x16x32_bf16 v[32:35], v[158:161], v[174:177], v[32:35]
	v_mfma_f32_16x16x32_bf16 v[20:23], v[142:145], v[182:185], v[20:23]
	v_mfma_f32_16x16x32_bf16 v[16:19], v[158:161], v[182:185], v[16:19]
	v_mfma_f32_16x16x32_bf16 v[4:7], v[142:145], v[190:193], v[4:7]
	v_mfma_f32_16x16x32_bf16 v[0:3], v[158:161], v[190:193], v[0:3]
	s_barrier
	s_add_i32 s30, 0, 0x18000
	s_add_i32 s31, 0, 0x1c000
	v_add_u32_e32 v126, s30, v232
	v_add_u32_e32 v158, s31, v232
	ds_read_b128 v[98:101], v126
	ds_read_b128 v[106:109], v126 offset:1024
	ds_read_b128 v[118:121], v126 offset:2048
	ds_read_b128 v[126:129], v126 offset:3072
	ds_read_b128 v[138:141], v158
	ds_read_b128 v[142:145], v158 offset:1024
	ds_read_b128 v[150:153], v158 offset:2048
	ds_read_b128 v[158:161], v158 offset:3072
	s_add_u32 s0, s0, s22
	s_addc_u32 s1, s1, 0
	s_mov_b32 m0, s14
	v_lshl_add_u64 v[246:247], s[0:1], 0, v[206:207]
	ds_read_b128 v[162:165], v234 offset:32768
	ds_read_b128 v[166:169], v234 offset:33792
	ds_read_b128 v[170:173], v234 offset:34816
	ds_read_b128 v[174:177], v234 offset:35840
	ds_read_b128 v[178:181], v234 offset:36864
	ds_read_b128 v[182:185], v234 offset:37888
	ds_read_b128 v[186:189], v234 offset:38912
	ds_read_b128 v[190:193], v234 offset:39936
	global_load_lds_dwordx4 v[246:247], off
	v_lshl_add_u64 v[246:247], s[0:1], 0, v[204:205]
	s_mov_b32 m0, s15
	s_nop 0
	global_load_lds_dwordx4 v[246:247], off
	s_waitcnt vmcnt(8)
	s_waitcnt lgkmcnt(0)
	s_barrier
	v_mfma_f32_16x16x32_bf16 v[154:157], v[98:101], v[162:165], v[154:157]
	v_mfma_f32_16x16x32_bf16 v[146:149], v[118:121], v[162:165], v[146:149]
	v_mfma_f32_16x16x32_bf16 v[122:125], v[98:101], v[170:173], v[122:125]
	v_mfma_f32_16x16x32_bf16 v[114:117], v[118:121], v[170:173], v[114:117]
	v_mfma_f32_16x16x32_bf16 v[92:95], v[98:101], v[178:181], v[92:95]
	v_mfma_f32_16x16x32_bf16 v[88:91], v[118:121], v[178:181], v[88:91]
	v_mfma_f32_16x16x32_bf16 v[76:79], v[98:101], v[186:189], v[76:79]
	v_mfma_f32_16x16x32_bf16 v[72:75], v[118:121], v[186:189], v[72:75]
	v_mfma_f32_16x16x32_bf16 v[154:157], v[106:109], v[166:169], v[154:157]
	v_mfma_f32_16x16x32_bf16 v[146:149], v[126:129], v[166:169], v[146:149]
	v_mfma_f32_16x16x32_bf16 v[122:125], v[106:109], v[174:177], v[122:125]
	v_mfma_f32_16x16x32_bf16 v[114:117], v[126:129], v[174:177], v[114:117]
	v_mfma_f32_16x16x32_bf16 v[92:95], v[106:109], v[182:185], v[92:95]
	v_mfma_f32_16x16x32_bf16 v[88:91], v[126:129], v[182:185], v[88:91]
	v_mfma_f32_16x16x32_bf16 v[76:79], v[106:109], v[190:193], v[76:79]
	v_mfma_f32_16x16x32_bf16 v[72:75], v[126:129], v[190:193], v[72:75]
	v_mfma_f32_16x16x32_bf16 v[134:137], v[138:141], v[162:165], v[134:137]
	v_mfma_f32_16x16x32_bf16 v[130:133], v[150:153], v[162:165], v[130:133]
	v_mfma_f32_16x16x32_bf16 v[110:113], v[138:141], v[170:173], v[110:113]
	v_mfma_f32_16x16x32_bf16 v[102:105], v[150:153], v[170:173], v[102:105]
	v_mfma_f32_16x16x32_bf16 v[84:87], v[138:141], v[178:181], v[84:87]
	v_mfma_f32_16x16x32_bf16 v[80:83], v[150:153], v[178:181], v[80:83]
	v_mfma_f32_16x16x32_bf16 v[68:71], v[138:141], v[186:189], v[68:71]
	v_mfma_f32_16x16x32_bf16 v[64:67], v[150:153], v[186:189], v[64:67]
	v_mfma_f32_16x16x32_bf16 v[134:137], v[142:145], v[166:169], v[134:137]
	v_mfma_f32_16x16x32_bf16 v[130:133], v[158:161], v[166:169], v[130:133]
	v_mfma_f32_16x16x32_bf16 v[110:113], v[142:145], v[174:177], v[110:113]
	v_mfma_f32_16x16x32_bf16 v[102:105], v[158:161], v[174:177], v[102:105]
	v_mfma_f32_16x16x32_bf16 v[84:87], v[142:145], v[182:185], v[84:87]
	v_mfma_f32_16x16x32_bf16 v[80:83], v[158:161], v[182:185], v[80:83]
	v_mfma_f32_16x16x32_bf16 v[68:71], v[142:145], v[190:193], v[68:71]
	v_mfma_f32_16x16x32_bf16 v[64:67], v[158:161], v[190:193], v[64:67]
	s_barrier
; #define PG8_STAGE(bufoff, gbase, voff) do { _Pragma("unroll") for (int _i = 0; _i < 2; ++_i) \
;         __builtin_amdgcn_global_load_lds((const unsigned*)((const char*)(gbase) + (voff)[_i]), (PG8_LAS unsigned*)(lds + (bufoff) + ldsw + _i * 8192), 16, 0, 0); } while (0)
; #define PG8_LDA(dst, b, h) do { _Pragma("unroll") for (int m = 0; m < 4; ++m) _Pragma("unroll") for (int k = 0; k < 2; ++k) dst[m][k] = *(const PG8_LAS bf16x8*)(lds + PG8_SA(b, h) + aoff + m * 2048 + k * 1024); } while (0)
; #define PG8_MMA(ai, bj, At, Bt) do { __builtin_amdgcn_s_setprio(1); _Pragma("unroll") for (int m = 0; m < 4; ++m) _Pragma("unroll") for (int n = 0; n < 2; ++n) _Pragma("unroll") for (int k = 0; k < 2; ++k) \
;         acc[ai][bj][m][n] = __builtin_amdgcn_mfma_f32_16x16x32_bf16(Bt[n][k], At[m][k], acc[ai][bj][m][n], 0, 0, 0); __builtin_amdgcn_s_setprio(0); } while (0)
; #define PG8_WAIT_V(n) asm volatile("s_waitcnt vmcnt(" #n ")" ::: "memory")
; #define PG8_WAIT_L(n) asm volatile("s_waitcnt lgkmcnt(" #n ")" ::: "memory")
; #define PG8_BAR __builtin_amdgcn_s_barrier()
; #define PG8_SCHED __builtin_amdgcn_sched_barrier(0)
; template <class Epi, class Sched, bool ALIGN_EPI = false, bool SP2 = false>
; __device__ __forceinline__ void gemm_phase(PG8_LAS unsigned char* lds, const Gemm g, const Sched& S, const Epi& E) {
;     ...
;             PG8_LDA(At, 1, 1); PG8_STAGE(PG8_SB(1, 0), b3, voffB); PG8_STAGE(PG8_SB(1, 1), b3 + hstep, voffB); PG8_STAGE(PG8_SA(1, 0), a3, voffA);
;             PG8_WAIT_V(8); PG8_WAIT_L(0); PG8_BAR; PG8_MMA(1, 0, At, B0); PG8_MMA(1, 1, At, B1); PG8_BAR; PG8_SCHED;
	s_add_i32 s0, s30, s2
	v_lshl_add_u64 v[212:213], v[212:213], 0, s[20:21]
	s_mov_b32 m0, s0
	ds_read_b128 v[162:165], v234 offset:49152
	ds_read_b128 v[166:169], v234 offset:50176
	ds_read_b128 v[170:173], v234 offset:51200
	ds_read_b128 v[174:177], v234 offset:52224
	ds_read_b128 v[178:181], v234 offset:53248
	ds_read_b128 v[182:185], v234 offset:54272
	ds_read_b128 v[186:189], v234 offset:55296
	ds_read_b128 v[190:193], v234 offset:56320
	global_load_lds_dwordx4 v[212:213], off
	v_lshl_add_u64 v[212:213], v[214:215], 0, s[20:21]
	s_add_i32 m0, s0, 0x2000
	s_add_i32 s0, s31, s2
	global_load_lds_dwordx4 v[212:213], off
	v_lshl_add_u64 v[212:213], v[228:229], 0, s[20:21]
	s_mov_b32 m0, s0
	s_nop 0
	global_load_lds_dwordx4 v[212:213], off
	v_lshl_add_u64 v[212:213], v[236:237], 0, s[20:21]
	s_add_i32 m0, s0, 0x2000
	s_nop 0
	global_load_lds_dwordx4 v[212:213], off
	v_lshl_add_u64 v[212:213], v[242:243], 0, s[20:21]
	s_mov_b32 m0, s19
	s_nop 0
	global_load_lds_dwordx4 v[212:213], off
	v_lshl_add_u64 v[212:213], v[244:245], 0, s[20:21]
	s_mov_b32 m0, s46
	s_nop 0
	global_load_lds_dwordx4 v[212:213], off
	s_waitcnt vmcnt(8)
	s_waitcnt lgkmcnt(0)
	s_barrier
	v_mfma_f32_16x16x32_bf16 v[60:63], v[98:101], v[162:165], v[60:63]
	v_mfma_f32_16x16x32_bf16 v[56:59], v[118:121], v[162:165], v[56:59]
	v_mfma_f32_16x16x32_bf16 v[44:47], v[98:101], v[170:173], v[44:47]
	v_mfma_f32_16x16x32_bf16 v[40:43], v[118:121], v[170:173], v[40:43]
	v_mfma_f32_16x16x32_bf16 v[28:31], v[98:101], v[178:181], v[28:31]
	v_mfma_f32_16x16x32_bf16 v[24:27], v[118:121], v[178:181], v[24:27]
	v_mfma_f32_16x16x32_bf16 v[12:15], v[98:101], v[186:189], v[12:15]
	v_mfma_f32_16x16x32_bf16 v[8:11], v[118:121], v[186:189], v[8:11]
	v_mfma_f32_16x16x32_bf16 v[60:63], v[106:109], v[166:169], v[60:63]
	v_mfma_f32_16x16x32_bf16 v[56:59], v[126:129], v[166:169], v[56:59]
	v_mfma_f32_16x16x32_bf16 v[44:47], v[106:109], v[174:177], v[44:47]
	v_mfma_f32_16x16x32_bf16 v[40:43], v[126:129], v[174:177], v[40:43]
	v_mfma_f32_16x16x32_bf16 v[28:31], v[106:109], v[182:185], v[28:31]
	v_mfma_f32_16x16x32_bf16 v[24:27], v[126:129], v[182:185], v[24:27]
	v_mfma_f32_16x16x32_bf16 v[12:15], v[106:109], v[190:193], v[12:15]
	v_mfma_f32_16x16x32_bf16 v[8:11], v[126:129], v[190:193], v[8:11]
	v_mfma_f32_16x16x32_bf16 v[52:55], v[138:141], v[162:165], v[52:55]
	v_mfma_f32_16x16x32_bf16 v[48:51], v[150:153], v[162:165], v[48:51]
	v_mfma_f32_16x16x32_bf16 v[36:39], v[138:141], v[170:173], v[36:39]
	v_mfma_f32_16x16x32_bf16 v[32:35], v[150:153], v[170:173], v[32:35]
	v_mfma_f32_16x16x32_bf16 v[20:23], v[138:141], v[178:181], v[20:23]
	v_mfma_f32_16x16x32_bf16 v[16:19], v[150:153], v[178:181], v[16:19]
	v_mfma_f32_16x16x32_bf16 v[4:7], v[138:141], v[186:189], v[4:7]
	v_mfma_f32_16x16x32_bf16 v[0:3], v[150:153], v[186:189], v[0:3]
	v_mfma_f32_16x16x32_bf16 v[52:55], v[142:145], v[166:169], v[52:55]
	v_mfma_f32_16x16x32_bf16 v[48:51], v[158:161], v[166:169], v[48:51]
	v_mfma_f32_16x16x32_bf16 v[36:39], v[142:145], v[174:177], v[36:39]
	v_mfma_f32_16x16x32_bf16 v[32:35], v[158:161], v[174:177], v[32:35]
	v_mfma_f32_16x16x32_bf16 v[20:23], v[142:145], v[182:185], v[20:23]
	v_mfma_f32_16x16x32_bf16 v[16:19], v[158:161], v[182:185], v[16:19]
	v_mfma_f32_16x16x32_bf16 v[4:7], v[142:145], v[190:193], v[4:7]
	v_mfma_f32_16x16x32_bf16 v[0:3], v[158:161], v[190:193], v[0:3]
	s_barrier
	s_add_u32 s17, s17, 0x100
	s_addc_u32 s23, s23, 0
	s_add_u32 s66, s66, 0x100
	s_addc_u32 s67, s67, 0
	s_cmp_ge_u32 s28, s49
	s_mov_b32 s0, s28
	s_cbranch_scc0 .LBB0_447
	s_and_b64 vcc, exec, s[62:63]
	s_cbranch_vccz .LBB0_450
	s_barrier

; #define PG8_STAGE(bufoff, gbase, voff) do { _Pragma("unroll") for (int _i = 0; _i < 2; ++_i) \
;         __builtin_amdgcn_global_load_lds((const unsigned*)((const char*)(gbase) + (voff)[_i]), (PG8_LAS unsigned*)(lds + (bufoff) + ldsw + _i * 8192), 16, 0, 0); } while (0)
; #define PG8_LDA(dst, b, h) do { _Pragma("unroll") for (int m = 0; m < 4; ++m) _Pragma("unroll") for (int k = 0; k < 2; ++k) dst[m][k] = *(const PG8_LAS bf16x8*)(lds + PG8_SA(b, h) + aoff + m * 2048 + k * 1024); } while (0)
; #define PG8_LDB(dst, b, h) do { _Pragma("unroll") for (int n = 0; n < 2; ++n) _Pragma("unroll") for (int k = 0; k < 2; ++k) dst[n][k] = *(const PG8_LAS bf16x8*)(lds + PG8_SB(b, h) + boff + n * 2048 + k * 1024); } while (0)
; #define PG8_MMA(ai, bj, At, Bt) do { __builtin_amdgcn_s_setprio(1); _Pragma("unroll") for (int m = 0; m < 4; ++m) _Pragma("unroll") for (int n = 0; n < 2; ++n) _Pragma("unroll") for (int k = 0; k < 2; ++k) \
;         acc[ai][bj][m][n] = __builtin_amdgcn_mfma_f32_16x16x32_bf16(Bt[n][k], At[m][k], acc[ai][bj][m][n], 0, 0, 0); __builtin_amdgcn_s_setprio(0); } while (0)
; #define PG8_WAIT_V(n) asm volatile("s_waitcnt vmcnt(" #n ")" ::: "memory")
; #define PG8_WAIT_L(n) asm volatile("s_waitcnt lgkmcnt(" #n ")" ::: "memory")
; template <class Epi, class Sched, bool ALIGN_EPI = false, bool SP2 = false>
; __device__ __forceinline__ void gemm_phase(PG8_LAS unsigned char* lds, const Gemm g, const Sched& S, const Epi& E) {
;     ...
;             const bool last = (t == nt - 2);
;             const char* a1 = cA + (size_t)(t + 1) * kstep;
;             const char* a2 = last ? nA : cA + (size_t)(t + 2) * kstep; const char* b2 = last ? nB : cB + (size_t)(t + 2) * kstep;
;             const char* a3 = a2 + kstep; const char* b3 = b2 + kstep;
;             if (last && has_next) S.a_ready(nxt);
;             if constexpr (SP2) {
;             PG8_LDB(B0, 0, 0); PG8_LDB(B1, 0, 1); PG8_SCHED; PG8_LDA(At, 0, 0); PG8_STAGE(PG8_SA(1, 1), a1 + hstep, voffA);
;             PG8_WAIT_V(8); PG8_WAIT_L(0); PG8_BAR; PG8_MMA(0, 0, At, B0); PG8_MMA(0, 1, At, B1); PG8_BAR; PG8_SCHED;
;             PG8_LDA(At, 0, 1); PG8_STAGE(PG8_SB(0, 0), b2, voffB); PG8_STAGE(PG8_SB(0, 1), b2 + hstep, voffB); PG8_STAGE(PG8_SA(0, 0), a2, voffA);
;             PG8_WAIT_V(8); PG8_WAIT_L(0); PG8_BAR; PG8_MMA(1, 0, At, B0); PG8_MMA(1, 1, At, B1); PG8_BAR; PG8_SCHED;
.LBB0_510:
	s_add_i32 s95, s0, 2
	s_add_u32 s96, s40, 0x80
	s_addc_u32 s1, s41, 0
	s_add_i32 vcc_lo, 0, 0x10000
	s_cmp_eq_u32 s7, s0
	s_cselect_b32 s1, s89, s1
	s_cselect_b32 s0, s88, s96
	s_cselect_b32 s97, s87, s94
	s_cselect_b32 s96, s86, s45
	s_add_i32 vcc_hi, 0, 0x14000
	v_add_u32_e32 v142, vcc_lo, v193
	v_add_u32_e32 v158, vcc_hi, v193
	ds_read_b128 v[130:133], v142
	ds_read_b128 v[134:137], v142 offset:1024
	ds_read_b128 v[138:141], v142 offset:2048
	ds_read_b128 v[142:145], v142 offset:3072
	ds_read_b128 v[146:149], v158
	ds_read_b128 v[150:153], v158 offset:1024
	ds_read_b128 v[154:157], v158 offset:2048
	ds_read_b128 v[158:161], v158 offset:3072
	v_lshl_add_u64 v[202:203], s[40:41], 0, v[188:189]
	s_add_i32 m0, s90, 0xc000
	ds_read_b128 v[162:165], v207
	ds_read_b128 v[166:169], v207 offset:1024
	ds_read_b128 v[170:173], v207 offset:2048
	ds_read_b128 v[174:177], v207 offset:3072
	ds_read_b128 v[208:211], v207 offset:4096
	ds_read_b128 v[212:215], v207 offset:5120
	ds_read_b128 v[232:235], v207 offset:6144
	ds_read_b128 v[242:245], v207 offset:7168
	global_load_lds_dwordx4 v[202:203], off
	v_lshl_add_u64 v[202:203], s[40:41], 0, v[186:187]
	s_add_i32 m0, s90, 0xe000
	s_nop 0
	global_load_lds_dwordx4 v[202:203], off
	s_waitcnt vmcnt(8)
	s_waitcnt lgkmcnt(0)
	s_barrier
	v_mfma_f32_16x16x32_bf16 v[126:129], v[130:133], v[162:165], v[126:129]
	v_mfma_f32_16x16x32_bf16 v[122:125], v[138:141], v[162:165], v[122:125]
	v_mfma_f32_16x16x32_bf16 v[114:117], v[130:133], v[170:173], v[114:117]
	v_mfma_f32_16x16x32_bf16 v[106:109], v[138:141], v[170:173], v[106:109]
	v_mfma_f32_16x16x32_bf16 v[98:101], v[130:133], v[208:211], v[98:101]
	v_mfma_f32_16x16x32_bf16 v[88:91], v[138:141], v[208:211], v[88:91]
	v_mfma_f32_16x16x32_bf16 v[80:83], v[130:133], v[232:235], v[80:83]
	v_mfma_f32_16x16x32_bf16 v[72:75], v[138:141], v[232:235], v[72:75]
	v_mfma_f32_16x16x32_bf16 v[126:129], v[134:137], v[166:169], v[126:129]
	v_mfma_f32_16x16x32_bf16 v[122:125], v[142:145], v[166:169], v[122:125]
	v_mfma_f32_16x16x32_bf16 v[114:117], v[134:137], v[174:177], v[114:117]
	v_mfma_f32_16x16x32_bf16 v[106:109], v[142:145], v[174:177], v[106:109]
	v_mfma_f32_16x16x32_bf16 v[98:101], v[134:137], v[212:215], v[98:101]
	v_mfma_f32_16x16x32_bf16 v[88:91], v[142:145], v[212:215], v[88:91]
	v_mfma_f32_16x16x32_bf16 v[80:83], v[134:137], v[242:245], v[80:83]
	v_mfma_f32_16x16x32_bf16 v[72:75], v[142:145], v[242:245], v[72:75]
	v_mfma_f32_16x16x32_bf16 v[118:121], v[146:149], v[162:165], v[118:121]
	v_mfma_f32_16x16x32_bf16 v[110:113], v[154:157], v[162:165], v[110:113]
	v_mfma_f32_16x16x32_bf16 v[102:105], v[146:149], v[170:173], v[102:105]
	v_mfma_f32_16x16x32_bf16 v[92:95], v[154:157], v[170:173], v[92:95]
	v_mfma_f32_16x16x32_bf16 v[84:87], v[146:149], v[208:211], v[84:87]
	v_mfma_f32_16x16x32_bf16 v[76:79], v[154:157], v[208:211], v[76:79]
	v_mfma_f32_16x16x32_bf16 v[68:71], v[146:149], v[232:235], v[68:71]
	v_mfma_f32_16x16x32_bf16 v[64:67], v[154:157], v[232:235], v[64:67]
	v_mfma_f32_16x16x32_bf16 v[118:121], v[150:153], v[166:169], v[118:121]
	v_mfma_f32_16x16x32_bf16 v[110:113], v[158:161], v[166:169], v[110:113]
	v_mfma_f32_16x16x32_bf16 v[102:105], v[150:153], v[174:177], v[102:105]
	v_mfma_f32_16x16x32_bf16 v[92:95], v[158:161], v[174:177], v[92:95]
	v_mfma_f32_16x16x32_bf16 v[84:87], v[150:153], v[212:215], v[84:87]
	v_mfma_f32_16x16x32_bf16 v[76:79], v[158:161], v[212:215], v[76:79]
	v_mfma_f32_16x16x32_bf16 v[68:71], v[150:153], v[242:245], v[68:71]
	v_mfma_f32_16x16x32_bf16 v[64:67], v[158:161], v[242:245], v[64:67]
	s_barrier
	s_add_i32 vcc_lo, vcc_lo, s4
	v_lshl_add_u64 v[202:203], s[96:97], 0, v[96:97]
	s_mov_b32 m0, vcc_lo
	ds_read_b128 v[162:165], v207 offset:16384
	ds_read_b128 v[166:169], v207 offset:17408
	ds_read_b128 v[170:173], v207 offset:18432
	ds_read_b128 v[174:177], v207 offset:19456
	ds_read_b128 v[208:211], v207 offset:20480
	ds_read_b128 v[212:215], v207 offset:21504
	ds_read_b128 v[232:235], v207 offset:22528
	ds_read_b128 v[242:245], v207 offset:23552
	global_load_lds_dwordx4 v[202:203], off
	s_add_i32 m0, vcc_lo, 0x2000
	v_lshl_add_u64 v[228:229], s[96:97], 0, v[178:179]
	s_add_u32 s96, s96, s28
	s_addc_u32 s97, s97, 0
	s_add_i32 vcc_lo, vcc_hi, s4
	global_load_lds_dwordx4 v[228:229], off
	v_lshl_add_u64 v[230:231], s[96:97], 0, v[96:97]
	s_mov_b32 m0, vcc_lo
	v_lshl_add_u64 v[246:247], s[96:97], 0, v[178:179]
	global_load_lds_dwordx4 v[230:231], off
	s_add_i32 m0, vcc_lo, 0x2000
	v_lshl_add_u64 v[248:249], s[0:1], 0, v[182:183]
	global_load_lds_dwordx4 v[246:247], off
	s_mov_b32 m0, s90
	v_lshl_add_u64 v[236:237], s[0:1], 0, v[180:181]
	global_load_lds_dwordx4 v[248:249], off
	s_mov_b32 m0, s8
	s_nop 0
	global_load_lds_dwordx4 v[236:237], off
	s_waitcnt vmcnt(8)
	s_waitcnt lgkmcnt(0)
	s_barrier
; #define PG8_STAGE(bufoff, gbase, voff) do { _Pragma("unroll") for (int _i = 0; _i < 2; ++_i) \
;         __builtin_amdgcn_global_load_lds((const unsigned*)((const char*)(gbase) + (voff)[_i]), (PG8_LAS unsigned*)(lds + (bufoff) + ldsw + _i * 8192), 16, 0, 0); } while (0)
; #define PG8_LDA(dst, b, h) do { _Pragma("unroll") for (int m = 0; m < 4; ++m) _Pragma("unroll") for (int k = 0; k < 2; ++k) dst[m][k] = *(const PG8_LAS bf16x8*)(lds + PG8_SA(b, h) + aoff + m * 2048 + k * 1024); } while (0)
; #define PG8_LDB(dst, b, h) do { _Pragma("unroll") for (int n = 0; n < 2; ++n) _Pragma("unroll") for (int k = 0; k < 2; ++k) dst[n][k] = *(const PG8_LAS bf16x8*)(lds + PG8_SB(b, h) + boff + n * 2048 + k * 1024); } while (0)
; #define PG8_MMA(ai, bj, At, Bt) do { __builtin_amdgcn_s_setprio(1); _Pragma("unroll") for (int m = 0; m < 4; ++m) _Pragma("unroll") for (int n = 0; n < 2; ++n) _Pragma("unroll") for (int k = 0; k < 2; ++k) \
;         acc[ai][bj][m][n] = __builtin_amdgcn_mfma_f32_16x16x32_bf16(Bt[n][k], At[m][k], acc[ai][bj][m][n], 0, 0, 0); __builtin_amdgcn_s_setprio(0); } while (0)
; #define PG8_WAIT_V(n) asm volatile("s_waitcnt vmcnt(" #n ")" ::: "memory")
; #define PG8_WAIT_L(n) asm volatile("s_waitcnt lgkmcnt(" #n ")" ::: "memory")
; #define PG8_BAR __builtin_amdgcn_s_barrier()
; #define PG8_SCHED __builtin_amdgcn_sched_barrier(0)
; template <class Epi, class Sched, bool ALIGN_EPI = false, bool SP2 = false>
; __device__ __forceinline__ void gemm_phase(PG8_LAS unsigned char* lds, const Gemm g, const Sched& S, const Epi& E) {
;     ...
;             PG8_WAIT_V(8); PG8_WAIT_L(0); PG8_BAR; PG8_MMA(1, 0, At, B0); PG8_MMA(1, 1, At, B1); PG8_BAR; PG8_SCHED;
;             PG8_LDB(B0, 1, 0); PG8_LDB(B1, 1, 1); PG8_SCHED; PG8_LDA(At, 1, 0); PG8_STAGE(PG8_SA(0, 1), a2 + hstep, voffA);
;             PG8_WAIT_V(8); PG8_WAIT_L(0); PG8_BAR; PG8_MMA(0, 0, At, B0); PG8_MMA(0, 1, At, B1); PG8_BAR; PG8_SCHED;
	v_mfma_f32_16x16x32_bf16 v[60:63], v[130:133], v[162:165], v[60:63]
	v_mfma_f32_16x16x32_bf16 v[56:59], v[138:141], v[162:165], v[56:59]
	v_mfma_f32_16x16x32_bf16 v[48:51], v[130:133], v[170:173], v[48:51]
	v_mfma_f32_16x16x32_bf16 v[40:43], v[138:141], v[170:173], v[40:43]
	v_mfma_f32_16x16x32_bf16 v[32:35], v[130:133], v[208:211], v[32:35]
	v_mfma_f32_16x16x32_bf16 v[24:27], v[138:141], v[208:211], v[24:27]
	v_mfma_f32_16x16x32_bf16 v[16:19], v[130:133], v[232:235], v[16:19]
	v_mfma_f32_16x16x32_bf16 v[8:11], v[138:141], v[232:235], v[8:11]
	v_mfma_f32_16x16x32_bf16 v[60:63], v[134:137], v[166:169], v[60:63]
	v_mfma_f32_16x16x32_bf16 v[56:59], v[142:145], v[166:169], v[56:59]
	v_mfma_f32_16x16x32_bf16 v[48:51], v[134:137], v[174:177], v[48:51]
	v_mfma_f32_16x16x32_bf16 v[40:43], v[142:145], v[174:177], v[40:43]
	v_mfma_f32_16x16x32_bf16 v[32:35], v[134:137], v[212:215], v[32:35]
	v_mfma_f32_16x16x32_bf16 v[24:27], v[142:145], v[212:215], v[24:27]
	v_mfma_f32_16x16x32_bf16 v[16:19], v[134:137], v[242:245], v[16:19]
	v_mfma_f32_16x16x32_bf16 v[8:11], v[142:145], v[242:245], v[8:11]
	v_mfma_f32_16x16x32_bf16 v[52:55], v[146:149], v[162:165], v[52:55]
	v_mfma_f32_16x16x32_bf16 v[44:47], v[154:157], v[162:165], v[44:47]
	v_mfma_f32_16x16x32_bf16 v[36:39], v[146:149], v[170:173], v[36:39]
	v_mfma_f32_16x16x32_bf16 v[28:31], v[154:157], v[170:173], v[28:31]
	v_mfma_f32_16x16x32_bf16 v[20:23], v[146:149], v[208:211], v[20:23]
	v_mfma_f32_16x16x32_bf16 v[12:15], v[154:157], v[208:211], v[12:15]
	v_mfma_f32_16x16x32_bf16 v[4:7], v[146:149], v[232:235], v[4:7]
	v_mfma_f32_16x16x32_bf16 v[0:3], v[154:157], v[232:235], v[0:3]
	v_mfma_f32_16x16x32_bf16 v[52:55], v[150:153], v[166:169], v[52:55]
	v_mfma_f32_16x16x32_bf16 v[44:47], v[158:161], v[166:169], v[44:47]
	v_mfma_f32_16x16x32_bf16 v[36:39], v[150:153], v[174:177], v[36:39]
	v_mfma_f32_16x16x32_bf16 v[28:31], v[158:161], v[174:177], v[28:31]
	v_mfma_f32_16x16x32_bf16 v[20:23], v[150:153], v[212:215], v[20:23]
	v_mfma_f32_16x16x32_bf16 v[12:15], v[158:161], v[212:215], v[12:15]
	v_mfma_f32_16x16x32_bf16 v[4:7], v[150:153], v[242:245], v[4:7]
	v_mfma_f32_16x16x32_bf16 v[0:3], v[158:161], v[242:245], v[0:3]
	s_barrier
	s_add_i32 s96, 0, 0x18000
	s_add_i32 s97, 0, 0x1c000
	v_add_u32_e32 v142, s96, v193
	v_add_u32_e32 v158, s97, v193
	ds_read_b128 v[130:133], v142
	ds_read_b128 v[134:137], v142 offset:1024
	ds_read_b128 v[138:141], v142 offset:2048
	ds_read_b128 v[142:145], v142 offset:3072
	ds_read_b128 v[146:149], v158
	ds_read_b128 v[150:153], v158 offset:1024
	ds_read_b128 v[154:157], v158 offset:2048
	ds_read_b128 v[158:161], v158 offset:3072
	s_add_u32 s0, s0, s28
	s_addc_u32 s1, s1, 0
	s_mov_b32 m0, s9
	v_lshl_add_u64 v[250:251], s[0:1], 0, v[182:183]
	ds_read_b128 v[162:165], v207 offset:32768
	ds_read_b128 v[166:169], v207 offset:33792
	ds_read_b128 v[170:173], v207 offset:34816
	ds_read_b128 v[174:177], v207 offset:35840
	ds_read_b128 v[208:211], v207 offset:36864
	ds_read_b128 v[212:215], v207 offset:37888
	ds_read_b128 v[232:235], v207 offset:38912
	ds_read_b128 v[242:245], v207 offset:39936
	global_load_lds_dwordx4 v[250:251], off
	v_lshl_add_u64 v[250:251], s[0:1], 0, v[180:181]
	s_mov_b32 m0, s33
	s_nop 0
	global_load_lds_dwordx4 v[250:251], off
	s_waitcnt vmcnt(8)
	s_waitcnt lgkmcnt(0)
	s_barrier
	v_mfma_f32_16x16x32_bf16 v[126:129], v[130:133], v[162:165], v[126:129]
	v_mfma_f32_16x16x32_bf16 v[122:125], v[138:141], v[162:165], v[122:125]
	v_mfma_f32_16x16x32_bf16 v[114:117], v[130:133], v[170:173], v[114:117]
	v_mfma_f32_16x16x32_bf16 v[106:109], v[138:141], v[170:173], v[106:109]
	v_mfma_f32_16x16x32_bf16 v[98:101], v[130:133], v[208:211], v[98:101]
	v_mfma_f32_16x16x32_bf16 v[88:91], v[138:141], v[208:211], v[88:91]
	v_mfma_f32_16x16x32_bf16 v[80:83], v[130:133], v[232:235], v[80:83]
	v_mfma_f32_16x16x32_bf16 v[72:75], v[138:141], v[232:235], v[72:75]
	v_mfma_f32_16x16x32_bf16 v[126:129], v[134:137], v[166:169], v[126:129]
	v_mfma_f32_16x16x32_bf16 v[122:125], v[142:145], v[166:169], v[122:125]
	v_mfma_f32_16x16x32_bf16 v[114:117], v[134:137], v[174:177], v[114:117]
	v_mfma_f32_16x16x32_bf16 v[106:109], v[142:145], v[174:177], v[106:109]
	v_mfma_f32_16x16x32_bf16 v[98:101], v[134:137], v[212:215], v[98:101]
	v_mfma_f32_16x16x32_bf16 v[88:91], v[142:145], v[212:215], v[88:91]
	v_mfma_f32_16x16x32_bf16 v[80:83], v[134:137], v[242:245], v[80:83]
	v_mfma_f32_16x16x32_bf16 v[72:75], v[142:145], v[242:245], v[72:75]
	v_mfma_f32_16x16x32_bf16 v[118:121], v[146:149], v[162:165], v[118:121]
	v_mfma_f32_16x16x32_bf16 v[110:113], v[154:157], v[162:165], v[110:113]
	v_mfma_f32_16x16x32_bf16 v[102:105], v[146:149], v[170:173], v[102:105]
	v_mfma_f32_16x16x32_bf16 v[92:95], v[154:157], v[170:173], v[92:95]
	v_mfma_f32_16x16x32_bf16 v[84:87], v[146:149], v[208:211], v[84:87]
	v_mfma_f32_16x16x32_bf16 v[76:79], v[154:157], v[208:211], v[76:79]
	v_mfma_f32_16x16x32_bf16 v[68:71], v[146:149], v[232:235], v[68:71]
	v_mfma_f32_16x16x32_bf16 v[64:67], v[154:157], v[232:235], v[64:67]
	v_mfma_f32_16x16x32_bf16 v[118:121], v[150:153], v[166:169], v[118:121]
	v_mfma_f32_16x16x32_bf16 v[110:113], v[158:161], v[166:169], v[110:113]
	v_mfma_f32_16x16x32_bf16 v[102:105], v[150:153], v[174:177], v[102:105]
	v_mfma_f32_16x16x32_bf16 v[92:95], v[158:161], v[174:177], v[92:95]
	v_mfma_f32_16x16x32_bf16 v[84:87], v[150:153], v[212:215], v[84:87]
	v_mfma_f32_16x16x32_bf16 v[76:79], v[158:161], v[212:215], v[76:79]
	v_mfma_f32_16x16x32_bf16 v[68:71], v[150:153], v[242:245], v[68:71]
	v_mfma_f32_16x16x32_bf16 v[64:67], v[158:161], v[242:245], v[64:67]
	s_barrier
; #define PG8_STAGE(bufoff, gbase, voff) do { _Pragma("unroll") for (int _i = 0; _i < 2; ++_i) \
;         __builtin_amdgcn_global_load_lds((const unsigned*)((const char*)(gbase) + (voff)[_i]), (PG8_LAS unsigned*)(lds + (bufoff) + ldsw + _i * 8192), 16, 0, 0); } while (0)
; #define PG8_LDA(dst, b, h) do { _Pragma("unroll") for (int m = 0; m < 4; ++m) _Pragma("unroll") for (int k = 0; k < 2; ++k) dst[m][k] = *(const PG8_LAS bf16x8*)(lds + PG8_SA(b, h) + aoff + m * 2048 + k * 1024); } while (0)
; #define PG8_MMA(ai, bj, At, Bt) do { __builtin_amdgcn_s_setprio(1); _Pragma("unroll") for (int m = 0; m < 4; ++m) _Pragma("unroll") for (int n = 0; n < 2; ++n) _Pragma("unroll") for (int k = 0; k < 2; ++k) \
;         acc[ai][bj][m][n] = __builtin_amdgcn_mfma_f32_16x16x32_bf16(Bt[n][k], At[m][k], acc[ai][bj][m][n], 0, 0, 0); __builtin_amdgcn_s_setprio(0); } while (0)
; #define PG8_WAIT_V(n) asm volatile("s_waitcnt vmcnt(" #n ")" ::: "memory")
; #define PG8_WAIT_L(n) asm volatile("s_waitcnt lgkmcnt(" #n ")" ::: "memory")
; #define PG8_BAR __builtin_amdgcn_s_barrier()
; #define PG8_SCHED __builtin_amdgcn_sched_barrier(0)
; template <class Epi, class Sched, bool ALIGN_EPI = false, bool SP2 = false>
; __device__ __forceinline__ void gemm_phase(PG8_LAS unsigned char* lds, const Gemm g, const Sched& S, const Epi& E) {
;     ...
;             PG8_LDA(At, 1, 1); PG8_STAGE(PG8_SB(1, 0), b3, voffB); PG8_STAGE(PG8_SB(1, 1), b3 + hstep, voffB); PG8_STAGE(PG8_SA(1, 0), a3, voffA);
;             PG8_WAIT_V(8); PG8_WAIT_L(0); PG8_BAR; PG8_MMA(1, 0, At, B0); PG8_MMA(1, 1, At, B1); PG8_BAR; PG8_SCHED;
	s_add_i32 s0, s96, s4
	v_lshl_add_u64 v[202:203], v[202:203], 0, s[20:21]
	s_mov_b32 m0, s0
	ds_read_b128 v[162:165], v207 offset:49152
	ds_read_b128 v[166:169], v207 offset:50176
	ds_read_b128 v[170:173], v207 offset:51200
	ds_read_b128 v[174:177], v207 offset:52224
	ds_read_b128 v[208:211], v207 offset:53248
	ds_read_b128 v[212:215], v207 offset:54272
	ds_read_b128 v[232:235], v207 offset:55296
	ds_read_b128 v[242:245], v207 offset:56320
	global_load_lds_dwordx4 v[202:203], off
	v_lshl_add_u64 v[202:203], v[228:229], 0, s[20:21]
	s_add_i32 m0, s0, 0x2000
	s_add_i32 s0, s97, s4
	global_load_lds_dwordx4 v[202:203], off
	v_lshl_add_u64 v[202:203], v[230:231], 0, s[20:21]
	s_mov_b32 m0, s0
	s_nop 0
	global_load_lds_dwordx4 v[202:203], off
	v_lshl_add_u64 v[202:203], v[246:247], 0, s[20:21]
	s_add_i32 m0, s0, 0x2000
	s_nop 0
	global_load_lds_dwordx4 v[202:203], off
	v_lshl_add_u64 v[202:203], v[248:249], 0, s[20:21]
	s_mov_b32 m0, s53
	s_nop 0
	global_load_lds_dwordx4 v[202:203], off
	v_lshl_add_u64 v[202:203], v[236:237], 0, s[20:21]
	s_mov_b32 m0, s93
	s_nop 0
	global_load_lds_dwordx4 v[202:203], off
	s_waitcnt vmcnt(8)
	s_waitcnt lgkmcnt(0)
	s_barrier
	v_mfma_f32_16x16x32_bf16 v[60:63], v[130:133], v[162:165], v[60:63]
	v_mfma_f32_16x16x32_bf16 v[56:59], v[138:141], v[162:165], v[56:59]
	v_mfma_f32_16x16x32_bf16 v[48:51], v[130:133], v[170:173], v[48:51]
	v_mfma_f32_16x16x32_bf16 v[40:43], v[138:141], v[170:173], v[40:43]
	v_mfma_f32_16x16x32_bf16 v[32:35], v[130:133], v[208:211], v[32:35]
	v_mfma_f32_16x16x32_bf16 v[24:27], v[138:141], v[208:211], v[24:27]
	v_mfma_f32_16x16x32_bf16 v[16:19], v[130:133], v[232:235], v[16:19]
	v_mfma_f32_16x16x32_bf16 v[8:11], v[138:141], v[232:235], v[8:11]
	v_mfma_f32_16x16x32_bf16 v[60:63], v[134:137], v[166:169], v[60:63]
	v_mfma_f32_16x16x32_bf16 v[56:59], v[142:145], v[166:169], v[56:59]
	v_mfma_f32_16x16x32_bf16 v[48:51], v[134:137], v[174:177], v[48:51]
	v_mfma_f32_16x16x32_bf16 v[40:43], v[142:145], v[174:177], v[40:43]
	v_mfma_f32_16x16x32_bf16 v[32:35], v[134:137], v[212:215], v[32:35]
	v_mfma_f32_16x16x32_bf16 v[24:27], v[142:145], v[212:215], v[24:27]
	v_mfma_f32_16x16x32_bf16 v[16:19], v[134:137], v[242:245], v[16:19]
	v_mfma_f32_16x16x32_bf16 v[8:11], v[142:145], v[242:245], v[8:11]
	v_mfma_f32_16x16x32_bf16 v[52:55], v[146:149], v[162:165], v[52:55]
	v_mfma_f32_16x16x32_bf16 v[44:47], v[154:157], v[162:165], v[44:47]
	v_mfma_f32_16x16x32_bf16 v[36:39], v[146:149], v[170:173], v[36:39]
	v_mfma_f32_16x16x32_bf16 v[28:31], v[154:157], v[170:173], v[28:31]
	v_mfma_f32_16x16x32_bf16 v[20:23], v[146:149], v[208:211], v[20:23]
	v_mfma_f32_16x16x32_bf16 v[12:15], v[154:157], v[208:211], v[12:15]
	v_mfma_f32_16x16x32_bf16 v[4:7], v[146:149], v[232:235], v[4:7]
	v_mfma_f32_16x16x32_bf16 v[0:3], v[154:157], v[232:235], v[0:3]
	v_mfma_f32_16x16x32_bf16 v[52:55], v[150:153], v[166:169], v[52:55]
	v_mfma_f32_16x16x32_bf16 v[44:47], v[158:161], v[166:169], v[44:47]
	v_mfma_f32_16x16x32_bf16 v[36:39], v[150:153], v[174:177], v[36:39]
	v_mfma_f32_16x16x32_bf16 v[28:31], v[158:161], v[174:177], v[28:31]
	v_mfma_f32_16x16x32_bf16 v[20:23], v[150:153], v[212:215], v[20:23]
	v_mfma_f32_16x16x32_bf16 v[12:15], v[158:161], v[212:215], v[12:15]
	v_mfma_f32_16x16x32_bf16 v[4:7], v[150:153], v[242:245], v[4:7]
	v_mfma_f32_16x16x32_bf16 v[0:3], v[158:161], v[242:245], v[0:3]
	s_barrier
	s_add_u32 s45, s45, 0x100
	s_addc_u32 s94, s94, 0
	s_add_u32 s40, s40, 0x100
	s_addc_u32 s41, s41, 0
	s_cmp_ge_u32 s95, s58
	s_mov_b32 s0, s95
	s_cbranch_scc0 .LBB0_510
	s_and_b64 vcc, exec, s[82:83]
	s_cbranch_vccz .LBB0_513
	s_barrier
